# attention: score clamp as one v_min with source negation (constant in an SGPR) instead of v_max+v_min, 31 of 32 sites
# speedup vs baseline: 1.0067x; 1.0067x over previous
; #define LAS __attribute__((address_space(3)))
; __device__ __forceinline__ void attn_phase(const bf16_t* Q, const bf16_t* KF, const bf16_t* V, bf16_t* VT, bf16_t* O, LAS unsigned char* lds, unsigned* ctr) {
;     const int tid__ = otid(); const int lane = tid__ & 63, wave = tid__ >> 6, c32 = lane & 31, hf = lane >> 5;
;     for (int bh = blockIdx.x; bh < 256; bh += gridDim.x) {
;         const int b = bh >> 4, h = bh & 15;
;         bf16_t* vtw = VT + (size_t)(b * 16 + h) * 64 * SEQ;
;         __syncthreads();
;         if (tid__ == 0) *ctr = 0u;
;         const bf16_t* kfw = KF + (size_t)(b * 16 + h) * 64 * SEQ;
;         {
;             LAS bf16_t* scr = (LAS bf16_t*)(lds + wave * 8704);
;             for (int st = wave * 4; st < wave * 4 + 4; ++st) {
;                 const int s0 = st * 64;
; #pragma unroll
;                 for (int j = 0; j < 8; ++j) { const int i = (lane >> 3) + 8 * j, c = lane & 7;
;                     const u32x4 w = *(const u32x4*)(V + (size_t)(b * SEQ + s0 + i) * D + h * 64 + 8 * c);
;                     *(LAS u32x2*)(scr + i * 68 + 8 * c) = (u32x2){w.x, w.y}; *(LAS u32x2*)(scr + i * 68 + 8 * c + 4) = (u32x2){w.z, w.w}; }
;                 asm volatile("s_waitcnt lgkmcnt(0)" ::: "memory");
; #pragma unroll
;                 for (int blk = 0; blk < 8; ++blk) { const int t32 = blk >> 2, db = (blk >> 1) & 1, ks = blk & 1;
;                     unsigned short e[8];
; #pragma unroll
;                     for (int k = 0; k < 8; ++k) e[k] = scr[(32 * t32 + 16 * ks + 8 * (k >> 2) + 4 * hf + (k & 3)) * 68 + db * 32 + c32];
;                     u32x4 w; w.x = e[0] | ((unsigned)e[1] << 16); w.y = e[2] | ((unsigned)e[3] << 16); w.z = e[4] | ((unsigned)e[5] << 16); w.w = e[6] | ((unsigned)e[7] << 16);
;                     *(u32x4*)(vtw + (size_t)((((st * 2 + t32) * 2 + db) * 2 + ks) * 64 + lane) * 8) = w; }
;                 asm volatile("s_waitcnt lgkmcnt(0)" ::: "memory");
;             }
;             asm volatile("s_waitcnt vmcnt(0)" ::: "memory"); __syncthreads();
;         }
;         const bf16_t* vtb = vtw;
;         for (;;) {
;             unsigned uq = 0u;
;             if (lane == 0) uq = atomicAdd(ctr, 1u);
;             uq = (unsigned)__builtin_amdgcn_readfirstlane((int)uq);
;             if (uq >= 64u) break;
;             const int qb = 63 - (int)uq, t0 = qb * 32;
;             bf16x8 qf[4];
; #pragma unroll
.LBB0_1735:
	s_or_b64 exec, exec, s[10:11]
	s_mov_b32 s98, 0x42a00000
	s_waitcnt lgkmcnt(0)
	v_mov_b32_e32 v0, v219
	s_andn2_b64 vcc, exec, s[20:21]
	s_barrier
	s_cbranch_vccnz .LBB0_1753
	v_ashrrev_i32_e32 v2, 6, v0
	s_movk_i32 s6, 0x2200
	v_and_b32_e32 v1, 63, v0
	v_and_b32_e32 v84, 31, v0
	v_cmp_eq_u32_e64 s[10:11], 0, v0
	v_mul_lo_u32 v3, v2, s6
	v_bfe_u32 v4, v0, 3, 3
	v_lshlrev_b32_e32 v5, 4, v0
	v_lshrrev_b32_e32 v0, 3, v0
	v_add_u32_e32 v3, 0, v3
	v_and_b32_e32 v64, 0x70, v5
	v_mov_b32_e32 v65, 0
	v_and_b32_e32 v0, 4, v0
	v_lshl_add_u64 v[66:67], s[18:19], 0, v[64:65]
	v_add_u32_e32 v5, v3, v64
	v_lshlrev_b32_e32 v64, 1, v0
	v_mul_u32_u24_e32 v6, 0x88, v0
	v_mul_u32_u24_e32 v7, 0x88, v4
	v_or_b32_e32 v8, 1, v0
	v_or_b32_e32 v9, 2, v0
	v_or_b32_e32 v10, 3, v0
	v_or_b32_e32 v11, 8, v0
	v_or_b32_e32 v12, 9, v0
	v_or_b32_e32 v13, 10, v0
	v_or_b32_e32 v14, 11, v0
	v_cmp_lt_u32_e64 s[16:17], v0, v84
	v_or_b32_e32 v15, 16, v0
	v_or_b32_e32 v16, 24, v0
	v_or_b32_e32 v18, 17, v0
	v_or_b32_e32 v19, 25, v0
	v_or_b32_e32 v21, 18, v0
	v_or_b32_e32 v22, 26, v0
	v_or_b32_e32 v24, 19, v0
	v_or_b32_e32 v0, 27, v0
	s_add_u32 s4, s54, 0xe000000
	v_lshl_add_u32 v3, v84, 1, v3
	v_mul_u32_u24_e32 v17, 0x88, v15
	v_mul_u32_u24_e32 v20, 0x88, v18
	v_mul_u32_u24_e32 v23, 0x88, v21
	v_mul_u32_u24_e32 v25, 0x88, v24
	v_cmp_lt_u32_e64 s[48:49], v0, v84
	v_lshlrev_b32_e32 v0, 8, v2
	v_add_u32_e32 v90, v5, v7
	s_addc_u32 s5, s55, 0
	s_mov_b32 s73, 0
	v_cmp_eq_u32_e64 s[12:13], 0, v1
	v_cmp_gt_u32_e64 s[14:15], 32, v1
	v_lshl_add_u64 v[68:69], s[68:69], 0, v[64:65]
	v_lshlrev_b32_e32 v85, 3, v1
	v_lshlrev_b32_e32 v86, 4, v1
	v_cmp_lt_u32_e64 s[18:19], v8, v84
	v_cmp_lt_u32_e64 s[20:21], v9, v84
	v_cmp_lt_u32_e64 s[22:23], v10, v84
	v_cmp_lt_u32_e64 s[24:25], v11, v84
	v_cmp_lt_u32_e64 s[26:27], v12, v84
	v_cmp_lt_u32_e64 s[28:29], v13, v84
	v_cmp_lt_u32_e64 s[30:31], v14, v84
	v_cmp_lt_u32_e64 s[34:35], v15, v84
	v_cmp_lt_u32_e64 s[36:37], v16, v84
	v_cmp_lt_u32_e64 s[38:39], v18, v84
	v_cmp_lt_u32_e64 s[40:41], v19, v84
	v_cmp_lt_u32_e64 s[42:43], v21, v84
	v_cmp_lt_u32_e64 s[44:45], v22, v84
	v_cmp_lt_u32_e64 s[46:47], v24, v84
	v_lshl_or_b32 v87, v2, 11, v1
	v_or3_b32 v88, v4, v0, 56
	s_lshl_b32 s6, s2, 7
	s_lshl_b32 s7, s50, 7
	v_or_b32_e32 v89, 0x3ec0, v1
	s_add_i32 s8, 0, 0x23014
	v_add_u32_e32 v91, 0x880, v90
	v_add_u32_e32 v92, 0xcc0, v90
	v_add_u32_e32 v93, 0x1100, v90
	v_add_u32_e32 v94, 0x1540, v90
	v_add_u32_e32 v95, 0x1980, v90
	v_add_u32_e32 v96, 0x1dc0, v90
	v_add_u32_e32 v97, v3, v6
	v_add_u32_e32 v98, v3, v17
	v_add_u32_e32 v99, v3, v20
	v_add_u32_e32 v100, v3, v23
	v_add_u32_e32 v101, v3, v25
	s_mov_b64 s[74:75], 0x800
	s_mov_b64 s[76:77], 0x400
	v_mbcnt_hi_u32_b32 v102, -1, v234
	s_mov_b32 s78, s2
	s_branch .LBB0_1738

; __device__ __forceinline__ void attn_phase(const bf16_t* Q, const bf16_t* KF, const bf16_t* V, bf16_t* VT, bf16_t* O, LAS unsigned char* lds, unsigned* ctr) {
;     ...
;                 f32x16 z = {0.f, 0.f, 0.f, 0.f, 0.f, 0.f, 0.f, 0.f, 0.f, 0.f, 0.f, 0.f, 0.f, 0.f, 0.f, 0.f};
; #pragma unroll
;                 for (int kd = 0; kd < 4; ++kd) z = __builtin_amdgcn_mfma_f32_32x32x16_bf16(kfn[kd], qf[kd], z, 0, 0, 0);
;                 { const int ktn = kt > 0 ? kt - 1 : kt;
; #pragma unroll
;                   for (int kd = 0; kd < 4; ++kd) kfn[kd] = *(const bf16x8*)(kfw + (size_t)((ktn * 4 + kd) * 64 + lane) * 8); }
;                 bf16x8 vf[2][2];
; #pragma unroll
;                 for (int db = 0; db < 2; ++db)
; #pragma unroll
;                     for (int ks = 0; ks < 2; ++ks) vf[db][ks] = *(const bf16x8*)(vtb + (size_t)((((kt * 2 + db) * 2 + ks) * 64) + lane) * 8);
;                 float be[16], om[16];
; #pragma unroll
;                 for (int r = 0; r < 16; ++r) { const float e = __builtin_amdgcn_exp2f(-fmaxf(z[r], -80.0f)); be[r] = __builtin_amdgcn_rcpf(1.0f + e); om[r] = e * be[r]; }
;                 if (kt == qb) {
; #pragma unroll
;                     for (int r = 0; r < 16; ++r) { const int sl = 8 * (r >> 2) + 4 * hf + (r & 3); const bool valid = sl < c32; be[r] = valid ? be[r] : 0.f; om[r] = valid ? om[r] : 1.0f; } }
;                 float bp[4], pbp[4];
; #pragma unroll
;                 for (int q = 0; q < 4; ++q) { bp[q] = (om[4 * q] * om[4 * q + 1]) * (om[4 * q + 2] * om[4 * q + 3]); pbp[q] = __shfl_xor(bp[q], 32); }
;                 float after = Pc; float att[16];
; #pragma unroll
;                 for (int q = 3; q >= 0; --q) {
;                     const float off = hf == 0 ? after * pbp[q] : after;
;                     const float e3 = off, e2 = e3 * om[4 * q + 3], e1 = e2 * om[4 * q + 2], e0 = e1 * om[4 * q + 1];
;                     att[4 * q + 3] = be[4 * q + 3] * e3; att[4 * q + 2] = be[4 * q + 2] * e2; att[4 * q + 1] = be[4 * q + 1] * e1; att[4 * q] = be[4 * q] * e0;
;                     after *= bp[q] * pbp[q];
;                 }
;                 Pc = after;
; #pragma unroll
;                 for (int ks = 0; ks < 2; ++ks) {
.LBB0_1749:
	s_or_b64 exec, exec, s[86:87]
	v_readfirstlane_b32 s79, v0
	s_cmp_gt_u32 s79, 63
	s_mov_b64 s[86:87], -1
	s_cbranch_scc1 .LBB0_1744
	s_sub_i32 s9, 63, s79
	s_lshl_b32 s63, s9, 12
	v_lshl_or_b32 v28, v85, 1, s63
	global_load_dwordx4 v[0:3], v28, s[82:83]
	global_load_dwordx4 v[48:51], v28, s[84:85]
	global_load_dwordx4 v[16:19], v28, s[82:83] offset:1024
	global_load_dwordx4 v[52:55], v28, s[84:85] offset:1024
	global_load_dwordx4 v[20:23], v28, s[82:83] offset:2048
	global_load_dwordx4 v[56:59], v28, s[84:85] offset:2048
	global_load_dwordx4 v[24:27], v28, s[82:83] offset:3072
	global_load_dwordx4 v[60:63], v28, s[84:85] offset:3072
	v_or_b32_e32 v28, s63, v86
	s_waitcnt vmcnt(6)
	v_mfma_f32_32x32x16_bf16 v[0:15], v[0:3], v[48:51], 0
	s_waitcnt vmcnt(4)
	v_mfma_f32_32x32x16_bf16 v[0:15], v[16:19], v[52:55], v[0:15]
	v_and_b32_e32 v17, 64, v102
	v_xor_b32_e32 v16, 32, v102
	v_add_u32_e32 v17, 64, v17
	v_cmp_lt_i32_e32 vcc, v16, v17
	s_nop 1
	v_cndmask_b32_e32 v16, v102, v16, vcc
	s_waitcnt vmcnt(2)
	v_mfma_f32_32x32x16_bf16 v[0:15], v[20:23], v[56:59], v[0:15]
	v_lshlrev_b32_e32 v104, 2, v16
	global_load_dwordx4 v[20:23], v28, s[80:81]
	global_load_dwordx4 v[32:35], v28, s[80:81] offset:1024
	global_load_dwordx4 v[16:19], v28, s[80:81] offset:2048
	global_load_dwordx4 v[36:39], v28, s[80:81] offset:3072
	s_waitcnt vmcnt(4)
	v_mfma_f32_32x32x16_bf16 v[0:15], v[24:27], v[60:63], v[0:15]
	s_nop 11
	v_min_f32_e64 v1, -v1, s98
	v_min_f32_e64 v4, -v4, s98
	v_min_f32_e64 v5, -v5, s98
	v_min_f32_e64 v6, -v6, s98
	v_min_f32_e64 v7, -v7, s98
	v_min_f32_e64 v0, -v0, s98
	v_min_f32_e64 v2, -v2, s98
	v_min_f32_e64 v3, -v3, s98
	v_exp_f32_e32 v25, v1
	v_exp_f32_e32 v28, v4
	v_exp_f32_e32 v29, v5
	v_exp_f32_e32 v30, v6
	v_exp_f32_e32 v31, v7
	v_exp_f32_e32 v24, v0
	v_exp_f32_e32 v26, v2
	v_exp_f32_e32 v27, v3
	v_min_f32_e64 v9, -v9, s98
	v_min_f32_e64 v12, -v12, s98
	v_min_f32_e64 v13, -v13, s98
	v_min_f32_e64 v14, -v14, s98
	v_min_f32_e64 v15, -v15, s98
	v_min_f32_e64 v8, -v8, s98
	v_min_f32_e64 v10, -v10, s98
	v_min_f32_e64 v11, -v11, s98
	v_exp_f32_e32 v3, v9
	v_exp_f32_e32 v0, v12
	v_exp_f32_e32 v2, v13
	v_exp_f32_e32 v4, v14
	v_exp_f32_e32 v6, v15
	v_add_f32_e32 v9, 1.0, v25
	v_add_f32_e32 v12, 1.0, v28
	v_add_f32_e32 v13, 1.0, v29
	v_add_f32_e32 v14, 1.0, v30
	v_add_f32_e32 v15, 1.0, v31
	v_exp_f32_e32 v1, v8
	v_exp_f32_e32 v5, v10
	v_exp_f32_e32 v7, v11
	v_add_f32_e32 v8, 1.0, v24
	v_add_f32_e32 v10, 1.0, v26
	v_add_f32_e32 v11, 1.0, v27
	v_rcp_f32_e32 v64, v9
	v_rcp_f32_e32 v12, v12
	v_rcp_f32_e32 v74, v13
	v_rcp_f32_e32 v14, v14
	v_rcp_f32_e32 v75, v15
	v_rcp_f32_e32 v47, v8
	v_rcp_f32_e32 v72, v10
	v_rcp_f32_e32 v73, v11
	v_mul_f32_e32 v25, v25, v64
	v_mul_f32_e32 v28, v28, v12
	v_mul_f32_e32 v29, v29, v74
	v_mul_f32_e32 v30, v30, v14
	v_mul_f32_e32 v31, v31, v75
	v_mul_f32_e32 v24, v24, v47
	v_mul_f32_e32 v26, v26, v72
	v_mul_f32_e32 v27, v27, v73
	v_cndmask_b32_e64 v80, 0, v14, s[28:29]
	v_cndmask_b32_e64 v81, 1.0, v25, s[18:19]
	v_cndmask_b32_e64 v14, 1.0, v28, s[24:25]
	v_cndmask_b32_e64 v25, 1.0, v29, s[26:27]
	v_cndmask_b32_e64 v29, 1.0, v30, s[28:29]
	v_cndmask_b32_e64 v105, 1.0, v31, s[30:31]
	v_cndmask_b32_e64 v79, 0, v12, s[24:25]
	v_cndmask_b32_e64 v12, 1.0, v24, s[16:17]
	v_cndmask_b32_e64 v82, 1.0, v26, s[20:21]
	v_cndmask_b32_e64 v83, 1.0, v27, s[22:23]
	v_mul_f32_e32 v14, v14, v25
	v_mul_f32_e32 v26, v29, v105
	v_add_f32_e32 v40, 1.0, v1
	v_add_f32_e32 v41, 1.0, v3
	v_add_f32_e32 v42, 1.0, v5
	v_add_f32_e32 v43, 1.0, v7
	v_add_f32_e32 v44, 1.0, v0
	v_add_f32_e32 v45, 1.0, v2
	v_add_f32_e32 v46, 1.0, v4
	v_mul_f32_e32 v12, v12, v81
	v_mul_f32_e32 v24, v82, v83
	v_mul_f32_e32 v26, v14, v26
	v_add_f32_e32 v14, 1.0, v6
	v_rcp_f32_e32 v9, v40
	v_rcp_f32_e32 v11, v41
	v_rcp_f32_e32 v13, v42
	v_rcp_f32_e32 v15, v43
	v_rcp_f32_e32 v8, v44
	v_rcp_f32_e32 v10, v45
	v_mul_f32_e32 v24, v12, v24
	v_rcp_f32_e32 v12, v46
	v_rcp_f32_e32 v14, v14
	v_pk_mul_f32 v[0:1], v[0:1], v[8:9]
	v_pk_mul_f32 v[2:3], v[2:3], v[10:11]
	v_pk_mul_f32 v[4:5], v[4:5], v[12:13]
	v_pk_mul_f32 v[6:7], v[6:7], v[14:15]
	v_cndmask_b32_e64 v1, 1.0, v1, s[34:35]
	v_cndmask_b32_e64 v0, 1.0, v0, s[36:37]
	v_cndmask_b32_e64 v41, 1.0, v3, s[38:39]
	v_cndmask_b32_e64 v40, 1.0, v2, s[40:41]
	v_cndmask_b32_e64 v43, 1.0, v5, s[42:43]
	v_cndmask_b32_e64 v42, 1.0, v4, s[44:45]
	v_cndmask_b32_e64 v45, 1.0, v7, s[46:47]
	v_cndmask_b32_e64 v44, 1.0, v6, s[48:49]
	v_pk_mul_f32 v[0:1], v[0:1], v[40:41]
	v_pk_mul_f32 v[2:3], v[42:43], v[44:45]
	v_cndmask_b32_e64 v76, 0, v47, s[16:17]
	v_pk_mul_f32 v[0:1], v[0:1], v[2:3]
	ds_bpermute_b32 v46, v104, v0
	ds_bpermute_b32 v47, v104, v1
	ds_bpermute_b32 v30, v104, v26
	v_cndmask_b32_e64 v77, 0, v72, s[20:21]
	v_cndmask_b32_e64 v78, 0, v73, s[22:23]
	s_waitcnt lgkmcnt(2)
	v_cndmask_b32_e64 v5, 1.0, v46, s[14:15]
	s_waitcnt lgkmcnt(1)
	v_pk_mul_f32 v[72:73], v[0:1], v[46:47]
	v_mul_f32_e32 v6, v5, v44
	v_mov_b32_e32 v27, v72
	v_mov_b32_e32 v31, v73
	v_cndmask_b32_e64 v2, 0, v10, s[40:41]
	v_mul_f32_e32 v7, v42, v6
	s_waitcnt lgkmcnt(0)
	v_pk_mul_f32 v[0:1], v[26:27], v[30:31]
	ds_bpermute_b32 v28, v104, v24
	v_mul_f32_e32 v42, v2, v7
	v_mul_f32_e32 v2, v1, v30
	v_cndmask_b32_e64 v3, 0, v12, s[44:45]
	v_cndmask_b32_e64 v2, v1, v2, s[14:15]
	v_cndmask_b32_e64 v4, 0, v14, s[48:49]
	v_mul_f32_e32 v111, v3, v6
	v_mul_f32_e32 v3, v105, v2
	v_mul_f32_e32 v44, v5, v4
	v_mul_f32_e32 v4, v29, v3
	v_cndmask_b32_e64 v74, 0, v74, s[26:27]
	v_cndmask_b32_e64 v75, 0, v75, s[30:31]
	v_mul_f32_e32 v5, v25, v4
	v_mov_b32_e32 v25, v0
	v_mov_b32_e32 v29, v1
	v_mul_f32_e32 v2, v75, v2
	v_mul_f32_e32 v4, v74, v4
	s_waitcnt lgkmcnt(0)
; __device__ __forceinline__ void attn_phase(const bf16_t* Q, const bf16_t* KF, const bf16_t* V, bf16_t* VT, bf16_t* O, LAS unsigned char* lds, unsigned* ctr) {
;     ...
;                 float after = Pc; float att[16];
; #pragma unroll
;                 for (int q = 3; q >= 0; --q) {
;                     const float off = hf == 0 ? after * pbp[q] : after;
;                     const float e3 = off, e2 = e3 * om[4 * q + 3], e1 = e2 * om[4 * q + 2], e0 = e1 * om[4 * q + 1];
;                     att[4 * q + 3] = be[4 * q + 3] * e3; att[4 * q + 2] = be[4 * q + 2] * e2; att[4 * q + 1] = be[4 * q + 1] * e1; att[4 * q] = be[4 * q] * e0;
;                     after *= bp[q] * pbp[q];
;                 }
;                 Pc = after;
; #pragma unroll
;                 for (int ks = 0; ks < 2; ++ks) {
;                     const bf16x8 pf = __builtin_bit_cast(bf16x8, (u32x4){cvt_pk_bf16(att[8 * ks], att[8 * ks + 1]), cvt_pk_bf16(att[8 * ks + 2], att[8 * ks + 3]), cvt_pk_bf16(att[8 * ks + 4], att[8 * ks + 5]), cvt_pk_bf16(att[8 * ks + 6], att[8 * ks + 7])});
;                     o0 = __builtin_amdgcn_mfma_f32_32x32x16_bf16(vf[0][ks], pf, o0, 0, 0, 0); o1 = __builtin_amdgcn_mfma_f32_32x32x16_bf16(vf[1][ks], pf, o1, 0, 0, 0); }
;                 if (__all(Pc == 0.0f)) break;
	v_pk_mul_f32 v[74:75], v[24:25], v[28:29]
	v_cndmask_b32_e64 v64, 0, v64, s[18:19]
	v_mul_f32_e32 v0, v75, v28
	v_cndmask_b32_e64 v0, v75, v0, s[14:15]
	v_mul_f32_e32 v1, v83, v0
	v_mul_f32_e32 v6, v82, v1
	v_mul_f32_e32 v40, v40, v7
	v_mul_f32_e32 v7, v81, v6
	v_mul_f32_e32 v3, v80, v3
	v_mul_f32_e32 v5, v79, v5
	v_mul_f32_e32 v0, v78, v0
	v_mul_f32_e32 v1, v77, v1
	v_mul_f32_e32 v6, v64, v6
	v_mul_f32_e32 v7, v76, v7
	v_cvt_pk_bf16_f32 v24, v7, v6
	v_cvt_pk_bf16_f32 v25, v1, v0
	v_cvt_pk_bf16_f32 v26, v5, v4
	v_cvt_pk_bf16_f32 v27, v3, v2
	v_cndmask_b32_e64 v106, 0, v9, s[34:35]
	v_cndmask_b32_e64 v107, 0, v11, s[38:39]
	v_cndmask_b32_e64 v108, 0, v13, s[42:43]
	v_cndmask_b32_e64 v109, 0, v15, s[46:47]
	v_cndmask_b32_e64 v110, 0, v8, s[36:37]
	s_waitcnt vmcnt(3)
	v_mfma_f32_32x32x16_bf16 v[0:15], v[20:23], v[24:27], 0
	v_mul_f32_e32 v20, v72, v47
	v_cndmask_b32_e64 v20, v72, v20, s[14:15]
	v_mul_f32_e32 v46, v110, v40
	v_mul_f32_e32 v40, v45, v20
	v_mul_f32_e32 v45, v109, v20
	v_mul_f32_e32 v43, v43, v40
	v_mul_f32_e32 v41, v41, v43
	s_waitcnt vmcnt(1)
	v_mfma_f32_32x32x16_bf16 v[16:31], v[16:19], v[24:27], 0
	v_mul_f32_e32 v47, v108, v40
	v_mul_f32_e32 v40, v107, v43
	v_mul_f32_e32 v41, v106, v41
	v_cvt_pk_bf16_f32 v40, v41, v40
	v_cvt_pk_bf16_f32 v41, v47, v45
	v_cvt_pk_bf16_f32 v42, v46, v42
	v_cvt_pk_bf16_f32 v43, v111, v44
	v_mul_f32_e32 v77, v74, v75
	v_cmp_eq_f32_e32 vcc, 0, v77
	v_mfma_f32_32x32x16_bf16 v[0:15], v[32:35], v[40:43], v[0:15]
	s_cmp_eq_u64 vcc, exec
	s_cselect_b64 s[86:87], -1, 0
	s_cmp_eq_u32 s79, 63
	s_cselect_b64 s[88:89], -1, 0
	s_or_b64 s[86:87], s[88:89], s[86:87]
	s_and_b64 vcc, exec, s[86:87]
	s_waitcnt vmcnt(0)
	v_mfma_f32_32x32x16_bf16 v[16:31], v[36:39], v[40:43], v[16:31]
	s_cbranch_vccnz .LBB0_1743
	s_lshl_b32 s63, s79, 12
	v_subrev_u32_e32 v32, s63, v86
	v_add_u32_e32 v64, 0x3e000, v32
	v_lshl_add_u64 v[32:33], s[82:83], 0, v[64:65]
	s_mov_b64 s[86:87], 0xc00
	s_sub_i32 s63, 62, s79
	s_sub_i32 s72, s79, 62
	s_lshl_b32 s79, s79, 8
	v_lshl_add_u64 v[78:79], v[32:33], 0, s[86:87]
	v_lshl_add_u64 v[80:81], v[32:33], 0, s[74:75]
	v_lshl_add_u64 v[74:75], v[32:33], 0, s[76:77]
	v_subrev_u32_e32 v72, s79, v89
	v_mov_b64_e32 v[82:83], v[64:65]
; __device__ __forceinline__ void attn_phase(const bf16_t* Q, const bf16_t* KF, const bf16_t* V, bf16_t* VT, bf16_t* O, LAS unsigned char* lds, unsigned* ctr) {
;     ...
;                 f32x16 z = {0.f, 0.f, 0.f, 0.f, 0.f, 0.f, 0.f, 0.f, 0.f, 0.f, 0.f, 0.f, 0.f, 0.f, 0.f, 0.f};
; #pragma unroll
;                 for (int kd = 0; kd < 4; ++kd) z = __builtin_amdgcn_mfma_f32_32x32x16_bf16(kfn[kd], qf[kd], z, 0, 0, 0);
;                 { const int ktn = kt > 0 ? kt - 1 : kt;
; #pragma unroll
;                   for (int kd = 0; kd < 4; ++kd) kfn[kd] = *(const bf16x8*)(kfw + (size_t)((ktn * 4 + kd) * 64 + lane) * 8); }
;                 bf16x8 vf[2][2];
; #pragma unroll
;                 for (int db = 0; db < 2; ++db)
; #pragma unroll
;                     for (int ks = 0; ks < 2; ++ks) vf[db][ks] = *(const bf16x8*)(vtb + (size_t)((((kt * 2 + db) * 2 + ks) * 64) + lane) * 8);
;                 float be[16], om[16];
; #pragma unroll
;                 for (int r = 0; r < 16; ++r) { const float e = __builtin_amdgcn_exp2f(-fmaxf(z[r], -80.0f)); be[r] = __builtin_amdgcn_rcpf(1.0f + e); om[r] = e * be[r]; }
;                 if (kt == qb) {
; #pragma unroll
;                     for (int r = 0; r < 16; ++r) { const int sl = 8 * (r >> 2) + 4 * hf + (r & 3); const bool valid = sl < c32; be[r] = valid ? be[r] : 0.f; om[r] = valid ? om[r] : 1.0f; } }
;                 float bp[4], pbp[4];
; #pragma unroll
;                 for (int q = 0; q < 4; ++q) { bp[q] = (om[4 * q] * om[4 * q + 1]) * (om[4 * q + 2] * om[4 * q + 3]); pbp[q] = __shfl_xor(bp[q], 32); }
;                 float after = Pc; float att[16];
; #pragma unroll
;                 for (int q = 3; q >= 0; --q) {
;                     const float off = hf == 0 ? after * pbp[q] : after;
;                     const float e3 = off, e2 = e3 * om[4 * q + 3], e1 = e2 * om[4 * q + 2], e0 = e1 * om[4 * q + 1];
;                     att[4 * q + 3] = be[4 * q + 3] * e3; att[4 * q + 2] = be[4 * q + 2] * e2; att[4 * q + 1] = be[4 * q + 1] * e1; att[4 * q] = be[4 * q] * e0;
;                     after *= bp[q] * pbp[q];
;                 }
;                 Pc = after;
; #pragma unroll
;                 for (int ks = 0; ks < 2; ++ks) {
.LBB0_1752:
	v_lshl_add_u64 v[32:33], s[82:83], 0, v[82:83]
	global_load_dwordx4 v[32:35], v[32:33], off
	s_nop 0
	global_load_dwordx4 v[106:109], v[74:75], off
	global_load_dwordx4 v[110:113], v[80:81], off
	global_load_dwordx4 v[114:117], v[78:79], off
	s_min_u32 s79, s63, 1
	s_lshl_b32 s79, s79, 8
	v_subrev_u32_e32 v36, s79, v72
	v_add_u32_e32 v38, 0xffffff40, v36
	v_ashrrev_i32_e32 v39, 31, v38
	v_lshlrev_b64 v[82:83], 4, v[38:39]
	v_add_u32_e32 v38, 0xffffff80, v36
	v_ashrrev_i32_e32 v39, 31, v38
	v_lshl_add_u64 v[74:75], v[38:39], 4, s[82:83]
	v_subrev_u32_e32 v38, 64, v36
	v_ashrrev_i32_e32 v39, 31, v38
	v_ashrrev_i32_e32 v37, 31, v36
	v_lshl_add_u64 v[80:81], v[38:39], 4, s[82:83]
	v_lshl_add_u64 v[78:79], v[36:37], 4, s[82:83]
	v_add_u32_e32 v64, 0xffffff40, v72
	v_mov_b32_e32 v73, v65
	v_lshl_add_u64 v[122:123], v[72:73], 4, s[80:81]
	s_waitcnt vmcnt(3)
	v_mfma_f32_32x32x16_bf16 v[32:47], v[32:35], v[48:51], 0
	global_load_dwordx4 v[122:125], v[122:123], off
	s_waitcnt vmcnt(3)
	v_mfma_f32_32x32x16_bf16 v[32:47], v[106:109], v[52:55], v[32:47]
	v_lshl_add_u64 v[106:107], v[64:65], 4, s[80:81]
	v_add_u32_e32 v64, 0xffffff80, v72
	global_load_dwordx4 v[106:109], v[106:107], off
	s_waitcnt vmcnt(3)
	v_mfma_f32_32x32x16_bf16 v[32:47], v[110:113], v[56:59], v[32:47]
	v_lshl_add_u64 v[110:111], v[64:65], 4, s[80:81]
	v_subrev_u32_e32 v64, 64, v72
	v_lshl_add_u64 v[118:119], v[64:65], 4, s[80:81]
	global_load_dwordx4 v[118:121], v[118:119], off
	v_add_u32_e32 v72, 0xffffff00, v72
	global_load_dwordx4 v[110:113], v[110:111], off
	s_waitcnt vmcnt(4)
	v_mfma_f32_32x32x16_bf16 v[32:47], v[114:117], v[60:63], v[32:47]
	s_nop 11
	v_min_f32_e64 v33, -v33, s98
	v_exp_f32_e32 v114, v33
	v_max_f32_e64 v33, -v34, -v34
	v_min_f32_e64 v34, -v35, s98
	v_exp_f32_e32 v115, v34
	v_min_f32_e64 v34, -v36, s98
	v_exp_f32_e32 v34, v34
	v_min_f32_e64 v32, -v32, s98
	v_exp_f32_e32 v32, v32
	v_add_f32_e32 v35, 1.0, v34
	v_rcp_f32_e32 v36, v35
	v_min_f32_e64 v35, -v37, s98
	v_exp_f32_e32 v35, v35
	v_min_f32_e32 v33, 0x42a00000, v33
	v_exp_f32_e32 v33, v33
	v_add_f32_e32 v37, 1.0, v35
	v_rcp_f32_e32 v64, v37
	s_nop 0
	v_mul_f32_e32 v116, v35, v64
	v_min_f32_e64 v35, -v38, s98
	v_exp_f32_e32 v35, v35
	s_nop 0
	v_add_f32_e32 v37, 1.0, v35
	v_rcp_f32_e32 v73, v37
	s_nop 0
	v_mul_f32_e32 v76, v35, v73
	v_min_f32_e64 v35, -v39, s98
	v_exp_f32_e32 v38, v35
	s_nop 0
	v_add_f32_e32 v35, 1.0, v38
	v_rcp_f32_e32 v126, v35
	v_min_f32_e64 v35, -v40, s98
	v_exp_f32_e32 v40, v35
	v_min_f32_e64 v35, -v41, s98
	v_exp_f32_e32 v41, v35
	v_add_f32_e32 v35, 1.0, v40
	v_rcp_f32_e32 v128, v35
	v_add_f32_e32 v35, 1.0, v41
	v_rcp_f32_e32 v129, v35
	v_min_f32_e64 v35, -v42, s98
	v_exp_f32_e32 v42, v35
	v_min_f32_e64 v35, -v43, s98
	v_exp_f32_e32 v43, v35
	v_add_f32_e32 v35, 1.0, v42
	v_rcp_f32_e32 v130, v35
	v_pk_mul_f32 v[40:41], v[40:41], v[128:129]
	v_add_f32_e32 v35, 1.0, v43
	v_rcp_f32_e32 v131, v35
	v_min_f32_e64 v35, -v44, s98
	v_exp_f32_e32 v44, v35
	v_min_f32_e64 v35, -v45, s98
	v_exp_f32_e32 v132, v35
	v_min_f32_e64 v35, -v46, s98
	v_exp_f32_e32 v45, v35
	v_min_f32_e64 v35, -v47, s98
	v_exp_f32_e32 v133, v35
	v_add_f32_e32 v35, 1.0, v32
	v_rcp_f32_e32 v46, v35
	v_add_f32_e32 v35, 1.0, v114
	v_rcp_f32_e32 v134, v35
	v_add_f32_e32 v35, 1.0, v33
	v_rcp_f32_e32 v47, v35
	v_add_f32_e32 v35, 1.0, v115
	v_rcp_f32_e32 v135, v35
	v_pk_mul_f32 v[42:43], v[42:43], v[130:131]
	v_pk_mul_f32 v[32:33], v[32:33], v[46:47]
	v_pk_mul_f32 v[138:139], v[40:41], v[40:41] op_sel_hi:[0,1]
	v_pk_mul_f32 v[114:115], v[114:115], v[134:135]
	v_pk_mul_f32 v[140:141], v[42:43], v[42:43] op_sel_hi:[0,1]
	v_pk_mul_f32 v[136:137], v[32:33], v[114:115]
	v_add_f32_e32 v32, 1.0, v44
	v_rcp_f32_e32 v142, v32
	v_add_f32_e32 v32, 1.0, v132
	v_rcp_f32_e32 v144, v32
	v_add_f32_e32 v32, 1.0, v45
	v_rcp_f32_e32 v143, v32
	v_add_f32_e32 v32, 1.0, v133
	v_rcp_f32_e32 v145, v32
	v_pk_mul_f32 v[44:45], v[44:45], v[142:143]
	v_pk_mul_f32 v[132:133], v[132:133], v[144:145]
	s_nop 0
	v_pk_mul_f32 v[146:147], v[44:45], v[132:133]
	s_nop 0
	v_pk_mul_f32 v[146:147], v[146:147], v[146:147] op_sel:[0,1] op_sel_hi:[1,0]
	ds_bpermute_b32 v127, v104, v146
	s_waitcnt lgkmcnt(0)
	v_mul_f32_e32 v32, v77, v127
	v_cndmask_b32_e64 v32, v77, v32, s[14:15]
	v_mul_f32_e32 v35, v32, v133
	v_mul_f32_e32 v37, v45, v35
	v_mul_f32_e32 v39, v132, v37
	v_mul_f32_e32 v105, v143, v35
	v_mul_f32_e32 v132, v144, v37
	v_mov_b32_e32 v35, v139
	v_mov_b32_e32 v37, v141
	v_pk_mul_f32 v[34:35], v[34:35], v[36:37]
	ds_bpermute_b32 v117, v104, v35
	v_mul_f32_e32 v133, v142, v39
	v_mov_b32_e32 v39, v146
	v_pk_mul_f32 v[38:39], v[38:39], v[126:127]
	v_mul_f32_e32 v40, v32, v145
	v_pk_mul_f32 v[44:45], v[76:77], v[38:39]
	s_waitcnt lgkmcnt(0)
	v_pk_mul_f32 v[34:35], v[34:35], v[116:117]
	v_mul_f32_e32 v32, v45, v117
	v_pk_mul_f32 v[34:35], v[34:35], v[44:45]
	ds_bpermute_b32 v37, v104, v34
	v_cndmask_b32_e64 v32, v45, v32, s[14:15]
	v_mul_f32_e32 v39, v43, v32
	v_mul_f32_e32 v43, v131, v32
	v_mul_f32_e32 v42, v42, v39
	s_waitcnt lgkmcnt(0)
	v_mul_f32_e32 v32, v35, v37
	v_cndmask_b32_e64 v32, v35, v32, s[14:15]
	v_mul_f32_e32 v38, v38, v32
	v_mul_f32_e32 v44, v130, v39
	v_mul_f32_e32 v39, v76, v38
	v_mul_f32_e32 v45, v116, v39
	v_mul_f32_e32 v73, v73, v38
	v_mul_f32_e32 v64, v64, v39
	v_mul_f32_e32 v45, v36, v45
	v_mov_b32_e32 v38, v136
	v_mov_b32_e32 v39, v34
	v_mov_b32_e32 v36, v137
	v_pk_mul_f32 v[36:37], v[38:39], v[36:37]
	ds_bpermute_b32 v34, v104, v36
	v_mul_f32_e32 v76, v126, v32
	v_mul_f32_e32 v41, v41, v42
	v_mul_f32_e32 v42, v129, v42
	v_mul_f32_e32 v41, v128, v41
	s_waitcnt lgkmcnt(0)
	v_pk_mul_f32 v[36:37], v[36:37], v[34:35]
	s_nop 0
	v_mul_f32_e32 v32, v37, v34
	v_cndmask_b32_e64 v32, v37, v32, s[14:15]
	v_mul_f32_e32 v34, v115, v32
	v_mul_f32_e32 v33, v33, v34
	v_mul_f32_e32 v35, v114, v33
	v_mul_f32_e32 v38, v135, v32
	v_mul_f32_e32 v34, v47, v34
	v_mul_f32_e32 v32, v134, v33
	v_mul_f32_e32 v33, v46, v35
	v_cvt_pk_bf16_f32 v32, v33, v32
	v_cvt_pk_bf16_f32 v33, v34, v38
	v_cvt_pk_bf16_f32 v34, v45, v64
	v_cvt_pk_bf16_f32 v35, v73, v76
	v_mul_f32_e32 v77, v36, v37
	v_cmp_eq_f32_e32 vcc, 0, v77
	s_waitcnt vmcnt(2)
	v_mfma_f32_32x32x16_bf16 v[0:15], v[106:109], v[32:35], v[0:15]
	s_cmp_lg_u64 vcc, exec
	s_cselect_b64 s[86:87], -1, 0
	s_add_i32 s63, s63, -1
	s_cmp_lg_u32 s72, 0
	s_cselect_b64 s[88:89], -1, 0
	s_and_b64 s[86:87], s[88:89], s[86:87]
	s_add_i32 s72, s72, 1
	s_waitcnt vmcnt(1)
	v_mfma_f32_32x32x16_bf16 v[16:31], v[118:121], v[32:35], v[16:31]
	v_cvt_pk_bf16_f32 v32, v41, v42
	v_cvt_pk_bf16_f32 v33, v44, v43
	v_cvt_pk_bf16_f32 v34, v133, v132
	v_cvt_pk_bf16_f32 v35, v105, v40
	s_and_b64 vcc, exec, s[86:87]
	s_waitcnt vmcnt(0)
	v_mfma_f32_32x32x16_bf16 v[0:15], v[110:113], v[32:35], v[0:15]
	v_mfma_f32_32x32x16_bf16 v[16:31], v[122:125], v[32:35], v[16:31]
	s_cbranch_vccnz .LBB0_1752
	s_branch .LBB0_1743

; #define LAS __attribute__((address_space(3)))
; __global__ void __launch_bounds__(NTHREADS, 2) fwd_megakernel(Params P) {
;     extern __shared__ __attribute__((aligned(16))) unsigned char lds_raw[];
;     LAS unsigned char* lds = (LAS unsigned char*)lds_raw;
	.amdhsa_kernel _Z14fwd_megakernel6Params
		.amdhsa_group_segment_fixed_size 0
		.amdhsa_private_segment_fixed_size 0
		.amdhsa_kernarg_size 1864
		.amdhsa_user_sgpr_count 2
		.amdhsa_user_sgpr_dispatch_ptr 0
		.amdhsa_user_sgpr_queue_ptr 0
		.amdhsa_user_sgpr_kernarg_segment_ptr 1
		.amdhsa_user_sgpr_dispatch_id 0
		.amdhsa_user_sgpr_kernarg_preload_length 0
		.amdhsa_user_sgpr_kernarg_preload_offset 0
		.amdhsa_user_sgpr_private_segment_size 0
		.amdhsa_uses_dynamic_stack 0
		.amdhsa_enable_private_segment 0
		.amdhsa_system_sgpr_workgroup_id_x 1
		.amdhsa_system_sgpr_workgroup_id_y 0
		.amdhsa_system_sgpr_workgroup_id_z 0
		.amdhsa_system_sgpr_workgroup_info 0
		.amdhsa_system_vgpr_workitem_id 2
		.amdhsa_next_free_vgpr 256
		.amdhsa_next_free_sgpr 102
		.amdhsa_accum_offset 256
		.amdhsa_reserve_vcc 1
		.amdhsa_float_round_mode_32 0
		.amdhsa_float_round_mode_16_64 0
		.amdhsa_float_denorm_mode_32 3
		.amdhsa_float_denorm_mode_16_64 3
		.amdhsa_dx10_clamp 1
		.amdhsa_ieee_mode 1
		.amdhsa_fp16_overflow 0
		.amdhsa_tg_split 0
		.amdhsa_exception_fp_ieee_invalid_op 0
		.amdhsa_exception_fp_denorm_src 0
		.amdhsa_exception_fp_ieee_div_zero 0
		.amdhsa_exception_fp_ieee_overflow 0
		.amdhsa_exception_fp_ieee_underflow 0
		.amdhsa_exception_fp_ieee_inexact 0
		.amdhsa_exception_int_div_zero 0
	.end_amdhsa_kernel

; #define LAS __attribute__((address_space(3)))
; __global__ void __launch_bounds__(NTHREADS, 2) fwd_megakernel(Params P) {
;     extern __shared__ __attribute__((aligned(16))) unsigned char lds_raw[];
;     LAS unsigned char* lds = (LAS unsigned char*)lds_raw;
amdhsa.kernels:
  - .agpr_count:     0
    .args:
      - .offset:         0
        .size:           1608
        .value_kind:     by_value
      - .offset:         1608
        .size:           4
        .value_kind:     hidden_block_count_x
      - .offset:         1612
        .size:           4
        .value_kind:     hidden_block_count_y
      - .offset:         1616
        .size:           4
        .value_kind:     hidden_block_count_z
      - .offset:         1620
        .size:           2
        .value_kind:     hidden_group_size_x
      - .offset:         1622
        .size:           2
        .value_kind:     hidden_group_size_y
      - .offset:         1624
        .size:           2
        .value_kind:     hidden_group_size_z
      - .offset:         1626
        .size:           2
        .value_kind:     hidden_remainder_x
      - .offset:         1628
        .size:           2
        .value_kind:     hidden_remainder_y
      - .offset:         1630
        .size:           2
        .value_kind:     hidden_remainder_z
      - .offset:         1648
        .size:           8
        .value_kind:     hidden_global_offset_x
      - .offset:         1656
        .size:           8
        .value_kind:     hidden_global_offset_y
      - .offset:         1664
        .size:           8
        .value_kind:     hidden_global_offset_z
      - .offset:         1672
        .size:           2
        .value_kind:     hidden_grid_dims
      - .offset:         1696
        .size:           8
        .value_kind:     hidden_multigrid_sync_arg
      - .offset:         1728
        .size:           4
        .value_kind:     hidden_dynamic_lds_size
    .group_segment_fixed_size: 0
    .kernarg_segment_align: 8
    .kernarg_segment_size: 1864
    .language:       OpenCL C
    .language_version:
      - 2
      - 0
    .max_flat_workgroup_size: 512
    .name:           _Z14fwd_megakernel6Params
    .private_segment_fixed_size: 0
    .sgpr_count:     108
    .sgpr_spill_count: 10
    .symbol:         _Z14fwd_megakernel6Params.kd
    .uniform_work_group_size: 1
    .uses_dynamic_stack: false
    .vgpr_count:     256
    .vgpr_spill_count: 0
    .wavefront_size: 64
